# S2 (SSD output) tile loops: packed f32 for the decay-exponent subtraction and the weight multiply (16 fewer VALU issues per tile)
# baseline (speedup 1.0000x reference)
.LBB0_1000:
	v_mul_u32_u24_e32 v150, 0x120, v158
	v_add_u32_e32 v142, s83, v2
	v_add_u32_e32 v97, v142, v150
	ds_read_b128 v[24:27], v97
	ds_read_b128 v[144:147], v97 offset:32
	ds_read_b128 v[152:155], v97 offset:64
	s_lshl_b32 s6, s3, 9
	s_add_i32 s13, s6, 0
	s_add_i32 s13, s13, 0x23000
	v_lshl_add_u32 v163, v158, 2, s13
	v_lshlrev_b32_e32 v160, 2, v119
	v_cmp_le_u32_e32 vcc, v160, v158
	s_waitcnt lgkmcnt(2)
	v_mfma_f32_32x32x16_bf16 v[20:35], v[24:27], v[20:23], 0
	s_waitcnt lgkmcnt(1)
	v_mfma_f32_32x32x16_bf16 v[20:35], v[144:147], v[88:91], v[20:35]
	s_waitcnt lgkmcnt(0)
	v_mfma_f32_32x32x16_bf16 v[20:35], v[152:155], v[92:95], v[20:35]
	ds_read_b128 v[88:91], v97 offset:96
	ds_read_b128 v[92:95], v97 offset:128
	s_waitcnt lgkmcnt(1)
	v_mfma_f32_32x32x16_bf16 v[20:35], v[88:91], v[80:83], v[20:35]
	s_waitcnt lgkmcnt(0)
	v_mfma_f32_32x32x16_bf16 v[20:35], v[92:95], v[84:87], v[20:35]
	ds_read_b128 v[80:83], v97 offset:160
	ds_read_b128 v[84:87], v97 offset:192
	s_waitcnt lgkmcnt(1)
	v_mfma_f32_32x32x16_bf16 v[20:35], v[80:83], v[72:75], v[20:35]
	ds_read_b32 v72, v163
	s_waitcnt lgkmcnt(1)
	v_mfma_f32_32x32x16_bf16 v[20:35], v[84:87], v[76:79], v[20:35]
	ds_read_b128 v[74:77], v97 offset:224
	s_waitcnt lgkmcnt(0)
	v_mfma_f32_32x32x16_bf16 v[20:35], v[74:77], v[68:71], v[20:35]
	v_lshl_add_u32 v209, v160, 2, s13
	ds_read_b128 v[220:223], v209
	ds_read_b128 v[224:227], v209 offset:32
	ds_read_b128 v[228:231], v209 offset:64
	ds_read_b128 v[232:235], v209 offset:96
	s_lshl_b32 s10, s3, 7
	v_sub_u32_e32 v208, v158, v160
	s_waitcnt lgkmcnt(0)
	v_pk_add_f32 v[220:221], v[72:73], v[220:221] op_sel_hi:[0,1] neg_lo:[0,1] neg_hi:[0,1]
	v_pk_add_f32 v[222:223], v[72:73], v[222:223] op_sel_hi:[0,1] neg_lo:[0,1] neg_hi:[0,1]
	v_pk_add_f32 v[224:225], v[72:73], v[224:225] op_sel_hi:[0,1] neg_lo:[0,1] neg_hi:[0,1]
	v_pk_add_f32 v[226:227], v[72:73], v[226:227] op_sel_hi:[0,1] neg_lo:[0,1] neg_hi:[0,1]
	v_pk_add_f32 v[228:229], v[72:73], v[228:229] op_sel_hi:[0,1] neg_lo:[0,1] neg_hi:[0,1]
	v_pk_add_f32 v[230:231], v[72:73], v[230:231] op_sel_hi:[0,1] neg_lo:[0,1] neg_hi:[0,1]
	v_pk_add_f32 v[232:233], v[72:73], v[232:233] op_sel_hi:[0,1] neg_lo:[0,1] neg_hi:[0,1]
	v_pk_add_f32 v[234:235], v[72:73], v[234:235] op_sel_hi:[0,1] neg_lo:[0,1] neg_hi:[0,1]
	v_exp_f32_e32 v220, v220
	v_exp_f32_e32 v221, v221
	v_exp_f32_e32 v222, v222
	v_exp_f32_e32 v223, v223
	v_exp_f32_e32 v224, v224
	v_exp_f32_e32 v225, v225
	v_exp_f32_e32 v226, v226
	v_exp_f32_e32 v227, v227
	v_exp_f32_e32 v228, v228
	v_exp_f32_e32 v229, v229
	v_exp_f32_e32 v230, v230
	v_exp_f32_e32 v231, v231
	v_exp_f32_e32 v232, v232
	v_exp_f32_e32 v233, v233
	v_exp_f32_e32 v234, v234
	v_exp_f32_e32 v235, v235
	v_cmp_le_i32_e32 vcc, 0, v208
	v_cmp_le_i32_e64 s[6:7], 1, v208
	s_nop 1
	v_cndmask_b32_e32 v220, 0, v220, vcc
	v_cndmask_b32_e64 v221, 0, v221, s[6:7]
	v_cmp_le_i32_e32 vcc, 2, v208
	v_cmp_le_i32_e64 s[6:7], 3, v208
	s_nop 1
	v_cndmask_b32_e32 v222, 0, v222, vcc
	v_cndmask_b32_e64 v223, 0, v223, s[6:7]
	v_cmp_le_i32_e32 vcc, 8, v208
	v_cmp_le_i32_e64 s[6:7], 9, v208
	s_nop 1
	v_cndmask_b32_e32 v224, 0, v224, vcc
	v_cndmask_b32_e64 v225, 0, v225, s[6:7]
	v_cmp_le_i32_e32 vcc, 10, v208
	v_cmp_le_i32_e64 s[6:7], 11, v208
	s_nop 1
	v_cndmask_b32_e32 v226, 0, v226, vcc
	v_cndmask_b32_e64 v227, 0, v227, s[6:7]
	v_cmp_le_i32_e32 vcc, 16, v208
	v_cmp_le_i32_e64 s[6:7], 17, v208
	s_nop 1
	v_cndmask_b32_e32 v228, 0, v228, vcc
	v_cndmask_b32_e64 v229, 0, v229, s[6:7]
	v_cmp_le_i32_e32 vcc, 18, v208
	v_cmp_le_i32_e64 s[6:7], 19, v208
	s_nop 1
	v_cndmask_b32_e32 v230, 0, v230, vcc
	v_cndmask_b32_e64 v231, 0, v231, s[6:7]
	v_cmp_le_i32_e32 vcc, 24, v208
	v_cmp_le_i32_e64 s[6:7], 25, v208
	s_nop 1
	v_cndmask_b32_e32 v232, 0, v232, vcc
	v_cndmask_b32_e64 v233, 0, v233, s[6:7]
	v_cmp_le_i32_e32 vcc, 26, v208
	v_cmp_le_i32_e64 s[6:7], 27, v208
	s_nop 1
	v_cndmask_b32_e32 v234, 0, v234, vcc
	v_cndmask_b32_e64 v235, 0, v235, s[6:7]
	v_pk_mul_f32 v[220:221], v[20:21], v[220:221]
	v_pk_mul_f32 v[222:223], v[22:23], v[222:223]
	v_pk_mul_f32 v[224:225], v[24:25], v[224:225]
	v_pk_mul_f32 v[226:227], v[26:27], v[226:227]
	v_pk_mul_f32 v[228:229], v[28:29], v[228:229]
	v_pk_mul_f32 v[230:231], v[30:31], v[230:231]
	v_pk_mul_f32 v[232:233], v[32:33], v[232:233]
	v_pk_mul_f32 v[234:235], v[34:35], v[234:235]
	v_exp_f32_e32 v34, v72
	s_lshl_b32 s12, s3, 6
	v_and_b32_e32 v151, 16, v100
	v_and_b32_e32 v153, 12, v118
	v_pk_mul_f32 v[18:19], v[18:19], v[34:35] op_sel_hi:[1,0]
	v_pk_mul_f32 v[16:17], v[16:17], v[34:35] op_sel_hi:[1,0]
	v_pk_mul_f32 v[14:15], v[14:15], v[34:35] op_sel_hi:[1,0]
	v_pk_mul_f32 v[12:13], v[12:13], v[34:35] op_sel_hi:[1,0]
	v_pk_mul_f32 v[10:11], v[10:11], v[34:35] op_sel_hi:[1,0]
	v_pk_mul_f32 v[8:9], v[8:9], v[34:35] op_sel_hi:[1,0]
	v_pk_mul_f32 v[6:7], v[6:7], v[34:35] op_sel_hi:[1,0]
	v_pk_mul_f32 v[4:5], v[4:5], v[34:35] op_sel_hi:[1,0]
	v_or3_b32 v35, v153, v151, s12
	v_bfe_u32 v152, v100, 2, 2
	v_lshrrev_b32_e32 v34, 3, v100
	v_or_b32_e32 v35, s14, v35
	v_lshl_add_u32 v143, v35, 1, 0
	v_and_or_b32 v144, v34, 4, v152
	v_cvt_pk_bf16_f32 v72, v224, v225
	v_cvt_pk_bf16_f32 v21, v230, v231
	v_mad_u32_u24 v30, v144, s33, v143
	v_cvt_pk_bf16_f32 v70, v220, v221
	v_cvt_pk_bf16_f32 v71, v222, v223
	v_cvt_pk_bf16_f32 v73, v226, v227
	v_cvt_pk_bf16_f32 v20, v228, v229
	v_cvt_pk_bf16_f32 v22, v232, v233
	v_cvt_pk_bf16_f32 v23, v234, v235
	ds_read_b64_tr_b16 v[24:25], v30
	ds_read_b64_tr_b16 v[26:27], v30 offset:4352
	ds_read_b64_tr_b16 v[28:29], v30 offset:8704
	ds_read_b64_tr_b16 v[30:31], v30 offset:13056
	s_waitcnt lgkmcnt(2)
	v_mfma_f32_32x32x16_bf16 v[4:19], v[24:27], v[70:73], v[4:19]
	s_lshl_b32 s7, s10, 2
	s_add_i32 s7, s7, 0
	v_lshl_add_u32 v35, v158, 2, s7
	v_add_u32_e32 v162, 0x23800, v35
	s_or_b32 s6, s14, s12
	v_or_b32_e32 v34, s6, v160
	v_mad_u32_u24 v145, v158, s33, 0
	s_waitcnt lgkmcnt(0)
	v_mfma_f32_32x32x16_bf16 v[4:19], v[28:31], v[20:23], v[4:19]
	ds_read_b32 v20, v162
	v_lshlrev_b32_e32 v159, 1, v34
	v_lshlrev_b32_e32 v32, 16, v120
	v_and_b32_e32 v33, 0xffff0000, v120
	s_lshl_b32 s6, s15, 9
	s_waitcnt lgkmcnt(0)
	v_div_scale_f32 v21, s[10:11], v20, v20, v101
	v_rcp_f32_e32 v22, v21
	s_add_i32 s6, s6, 0
	s_add_i32 s6, s6, 0x24000
	v_lshl_add_u32 v161, v158, 2, s6
	v_fma_f32 v23, -v21, v22, 1.0
	v_fmac_f32_e32 v22, v23, v22
	v_div_scale_f32 v23, vcc, v101, v20, v101
	v_mul_f32_e32 v24, v23, v22
	v_fma_f32 v25, -v21, v24, v23
	v_fmac_f32_e32 v24, v25, v22
	v_fma_f32 v21, -v21, v24, v23
	v_div_fmas_f32 v21, v21, v22, v24
	v_div_fixup_f32 v24, v21, v20, v101
	v_add_u32_e32 v20, v145, v159
	v_mul_f32_e32 v25, 0xbfb8aa3b, v32
	ds_read2_b64 v[26:29], v20 offset1:2
	ds_read2_b64 v[20:23], v20 offset0:4 offset1:6
	v_exp_f32_e32 v25, v25
	s_waitcnt lgkmcnt(1)
	v_lshlrev_b32_e32 v30, 16, v26
	v_and_b32_e32 v31, 0xffff0000, v26
	v_add_f32_e32 v25, 1.0, v25
	v_rcp_f32_e32 v34, v25
	v_pk_fma_f32 v[4:5], v[24:25], v[30:31], v[4:5] op_sel_hi:[0,1,1]
	v_mul_f32_e32 v25, 0xbfb8aa3b, v33
	v_exp_f32_e32 v25, v25
	v_lshlrev_b32_e32 v26, 16, v27
	v_and_b32_e32 v27, 0xffff0000, v27
	v_add_f32_e32 v25, 1.0, v25
	v_rcp_f32_e32 v35, v25
	s_nop 0
	v_pk_mul_f32 v[30:31], v[34:35], v[32:33]
	s_nop 0
	v_pk_mul_f32 v[118:119], v[30:31], v[4:5]
	v_lshlrev_b32_e32 v30, 16, v121
	v_mul_f32_e32 v25, 0xbfb8aa3b, v30
	v_exp_f32_e32 v25, v25
	v_and_b32_e32 v31, 0xffff0000, v121
	v_pk_mul_f32 v[4:5], v[118:119], v[118:119]
	v_add_f32_e32 v25, 1.0, v25
	v_rcp_f32_e32 v32, v25
	v_pk_fma_f32 v[6:7], v[24:25], v[26:27], v[6:7] op_sel_hi:[0,1,1]
	v_mul_f32_e32 v25, 0xbfb8aa3b, v31
	v_exp_f32_e32 v25, v25
	v_add_f32_e32 v4, v4, v5
	v_mov_b32_e32 v5, v0
	v_add_f32_e32 v25, 1.0, v25
	v_rcp_f32_e32 v33, v25
	v_lshlrev_b32_e32 v5, 2, v5
	v_bitop3_b32 v5, v5, s93, v252 bitop3:0x6c
	v_pk_mul_f32 v[26:27], v[32:33], v[30:31]
	v_lshlrev_b32_e32 v30, 16, v124
	v_mul_f32_e32 v25, 0xbfb8aa3b, v30
	v_exp_f32_e32 v25, v25
	v_pk_mul_f32 v[120:121], v[26:27], v[6:7]
	v_lshlrev_b32_e32 v26, 16, v28
	v_and_b32_e32 v27, 0xffff0000, v28
	v_and_b32_e32 v31, 0xffff0000, v124
	v_add_f32_e32 v25, 1.0, v25
	v_rcp_f32_e32 v32, v25
	v_pk_fma_f32 v[8:9], v[24:25], v[26:27], v[8:9] op_sel_hi:[0,1,1]
	v_mul_f32_e32 v25, 0xbfb8aa3b, v31
	v_exp_f32_e32 v25, v25
	v_lshlrev_b32_e32 v28, 16, v125
	v_pk_mul_f32 v[6:7], v[120:121], v[120:121]
	v_add_f32_e32 v25, 1.0, v25
	v_rcp_f32_e32 v33, v25
	v_mul_f32_e32 v25, 0xbfb8aa3b, v28
	v_exp_f32_e32 v25, v25
	v_add_f32_e32 v4, v6, v4
	v_pk_mul_f32 v[26:27], v[32:33], v[30:31]
	v_add_f32_e32 v4, v7, v4
	v_pk_mul_f32 v[122:123], v[26:27], v[8:9]
	v_lshlrev_b32_e32 v26, 16, v29
	v_and_b32_e32 v27, 0xffff0000, v29
	v_and_b32_e32 v29, 0xffff0000, v125
	v_add_f32_e32 v25, 1.0, v25
	v_rcp_f32_e32 v30, v25
	v_pk_fma_f32 v[10:11], v[24:25], v[26:27], v[10:11] op_sel_hi:[0,1,1]
	v_mul_f32_e32 v25, 0xbfb8aa3b, v29
	v_exp_f32_e32 v25, v25
	v_pk_mul_f32 v[8:9], v[122:123], v[122:123]
	v_add_f32_e32 v25, 1.0, v25
	v_rcp_f32_e32 v31, v25
	v_add_f32_e32 v4, v8, v4
	v_add_f32_e32 v4, v9, v4
	v_pk_mul_f32 v[26:27], v[30:31], v[28:29]
	v_lshlrev_b32_e32 v28, 16, v128
	v_pk_mul_f32 v[124:125], v[26:27], v[10:11]
	s_waitcnt lgkmcnt(0)
	v_lshlrev_b32_e32 v26, 16, v20
	v_and_b32_e32 v27, 0xffff0000, v20
	v_mul_f32_e32 v20, 0xbfb8aa3b, v28
	v_exp_f32_e32 v20, v20
	v_and_b32_e32 v29, 0xffff0000, v128
	v_pk_fma_f32 v[12:13], v[24:25], v[26:27], v[12:13] op_sel_hi:[0,1,1]
	v_pk_mul_f32 v[10:11], v[124:125], v[124:125]
	v_add_f32_e32 v20, 1.0, v20
	v_rcp_f32_e32 v30, v20
	v_mul_f32_e32 v20, 0xbfb8aa3b, v29
	v_exp_f32_e32 v20, v20
	v_add_f32_e32 v4, v10, v4
	v_add_f32_e32 v4, v11, v4
	v_add_f32_e32 v20, 1.0, v20
	v_rcp_f32_e32 v31, v20
	v_lshlrev_b32_e32 v20, 16, v21
	v_and_b32_e32 v21, 0xffff0000, v21
	v_pk_mul_f32 v[26:27], v[30:31], v[28:29]
	s_nop 0
	v_pk_mul_f32 v[126:127], v[26:27], v[12:13]
	v_lshlrev_b32_e32 v26, 16, v129
	v_mul_f32_e32 v25, 0xbfb8aa3b, v26
	v_exp_f32_e32 v25, v25
	v_and_b32_e32 v27, 0xffff0000, v129
	v_pk_mul_f32 v[12:13], v[126:127], v[126:127]
	v_add_f32_e32 v25, 1.0, v25
	v_pk_fma_f32 v[14:15], v[24:25], v[20:21], v[14:15] op_sel_hi:[0,1,1]
	v_mul_f32_e32 v20, 0xbfb8aa3b, v27
	v_exp_f32_e32 v20, v20
	v_rcp_f32_e32 v28, v25
	v_add_f32_e32 v4, v12, v4
	v_add_f32_e32 v4, v13, v4
	v_add_f32_e32 v20, 1.0, v20
	v_rcp_f32_e32 v29, v20
	s_nop 0
	v_pk_mul_f32 v[20:21], v[28:29], v[26:27]
	v_lshlrev_b32_e32 v26, 16, v134
	v_pk_mul_f32 v[128:129], v[20:21], v[14:15]
	v_lshlrev_b32_e32 v20, 16, v22
	v_and_b32_e32 v21, 0xffff0000, v22
	v_and_b32_e32 v27, 0xffff0000, v134
	v_mul_f32_e32 v22, 0xbfb8aa3b, v26
	v_exp_f32_e32 v22, v22
	v_pk_fma_f32 v[16:17], v[24:25], v[20:21], v[16:17] op_sel_hi:[0,1,1]
	v_mul_f32_e32 v20, 0xbfb8aa3b, v27
	v_exp_f32_e32 v20, v20
	v_add_f32_e32 v22, 1.0, v22
	v_rcp_f32_e32 v28, v22
	v_lshlrev_b32_e32 v22, 16, v135
	v_add_f32_e32 v20, 1.0, v20
	v_rcp_f32_e32 v29, v20
	v_mul_f32_e32 v25, 0xbfb8aa3b, v22
	v_exp_f32_e32 v25, v25
	v_pk_mul_f32 v[14:15], v[128:129], v[128:129]
	v_pk_mul_f32 v[20:21], v[28:29], v[26:27]
	v_add_f32_e32 v4, v14, v4
	v_pk_mul_f32 v[132:133], v[20:21], v[16:17]
	v_lshlrev_b32_e32 v20, 16, v23
	v_and_b32_e32 v21, 0xffff0000, v23
	v_and_b32_e32 v23, 0xffff0000, v135
	v_add_f32_e32 v25, 1.0, v25
	v_pk_fma_f32 v[18:19], v[24:25], v[20:21], v[18:19] op_sel_hi:[0,1,1]
	v_mul_f32_e32 v20, 0xbfb8aa3b, v23
	v_exp_f32_e32 v20, v20
	v_rcp_f32_e32 v26, v25
	v_pk_mul_f32 v[16:17], v[132:133], v[132:133]
	v_add_f32_e32 v4, v15, v4
	v_add_f32_e32 v20, 1.0, v20
	v_rcp_f32_e32 v27, v20
	v_add_f32_e32 v4, v16, v4
	v_add_f32_e32 v4, v17, v4
	v_pk_mul_f32 v[20:21], v[26:27], v[22:23]
	s_nop 0
	v_pk_mul_f32 v[134:135], v[20:21], v[18:19]
	s_nop 0
	v_pk_mul_f32 v[18:19], v[134:135], v[134:135]
	s_nop 0
	v_add_f32_e32 v4, v18, v4
	v_add_f32_e32 v4, v19, v4
	ds_bpermute_b32 v5, v5, v4
	s_and_saveexec_b64 s[6:7], s[4:5]
	s_cbranch_execz .LBB0_1034
	s_waitcnt lgkmcnt(0)
	v_add_f32_e32 v4, v4, v5
	ds_write_b32 v161, v4

.LBB0_1038:
	v_or_b32_e32 v208, s15, v158
	v_or_b32_e32 v210, s15, v160
	v_or_b32_e32 v211, s15, v144
	v_mad_u32_u24 v208, v208, s53, v142
	v_lshl_add_u32 v209, v210, 2, s13
	v_mad_u32_u24 v211, v211, s33, v143
	ds_read_b128 v[176:179], v208
	ds_read_b128 v[180:183], v208 offset:32
	ds_read_b128 v[184:187], v208 offset:64
	ds_read_b128 v[188:191], v208 offset:96
	ds_read_b128 v[192:195], v208 offset:128
	ds_read_b128 v[196:199], v208 offset:160
	ds_read_b128 v[200:203], v208 offset:192
	ds_read_b128 v[204:207], v208 offset:224
	ds_read_b128 v[220:223], v209
	ds_read_b128 v[224:227], v209 offset:32
	ds_read_b128 v[228:231], v209 offset:64
	ds_read_b128 v[232:235], v209 offset:96
	s_waitcnt lgkmcnt(11)
	v_mfma_f32_32x32x16_bf16 v[20:35], v[176:179], v[68:71], 0
	s_waitcnt lgkmcnt(10)
	v_mfma_f32_32x32x16_bf16 v[20:35], v[180:183], v[72:75], v[20:35]
	s_waitcnt lgkmcnt(9)
	v_mfma_f32_32x32x16_bf16 v[20:35], v[184:187], v[76:79], v[20:35]
	s_waitcnt lgkmcnt(8)
	v_mfma_f32_32x32x16_bf16 v[20:35], v[188:191], v[80:83], v[20:35]
	s_waitcnt lgkmcnt(7)
	v_mfma_f32_32x32x16_bf16 v[20:35], v[192:195], v[84:87], v[20:35]
	s_waitcnt lgkmcnt(6)
	v_mfma_f32_32x32x16_bf16 v[20:35], v[196:199], v[88:91], v[20:35]
	s_waitcnt lgkmcnt(5)
	v_mfma_f32_32x32x16_bf16 v[20:35], v[200:203], v[92:95], v[20:35]
	s_waitcnt lgkmcnt(4)
	v_mfma_f32_32x32x16_bf16 v[20:35], v[204:207], v[96:99], v[20:35]
	ds_read_b64_tr_b16 v[236:237], v211
	ds_read_b64_tr_b16 v[238:239], v211 offset:4352
	ds_read_b64_tr_b16 v[240:241], v211 offset:8704
	ds_read_b64_tr_b16 v[242:243], v211 offset:13056
	s_waitcnt lgkmcnt(4)
	v_pk_add_f32 v[220:221], v[146:147], v[220:221] op_sel_hi:[0,1] neg_lo:[0,1] neg_hi:[0,1]
	v_pk_add_f32 v[222:223], v[146:147], v[222:223] op_sel_hi:[0,1] neg_lo:[0,1] neg_hi:[0,1]
	v_pk_add_f32 v[224:225], v[146:147], v[224:225] op_sel_hi:[0,1] neg_lo:[0,1] neg_hi:[0,1]
	v_pk_add_f32 v[226:227], v[146:147], v[226:227] op_sel_hi:[0,1] neg_lo:[0,1] neg_hi:[0,1]
	v_pk_add_f32 v[228:229], v[146:147], v[228:229] op_sel_hi:[0,1] neg_lo:[0,1] neg_hi:[0,1]
	v_pk_add_f32 v[230:231], v[146:147], v[230:231] op_sel_hi:[0,1] neg_lo:[0,1] neg_hi:[0,1]
	v_pk_add_f32 v[232:233], v[146:147], v[232:233] op_sel_hi:[0,1] neg_lo:[0,1] neg_hi:[0,1]
	v_pk_add_f32 v[234:235], v[146:147], v[234:235] op_sel_hi:[0,1] neg_lo:[0,1] neg_hi:[0,1]
	v_exp_f32_e32 v220, v220
	v_exp_f32_e32 v221, v221
	v_exp_f32_e32 v222, v222
	v_exp_f32_e32 v223, v223
	v_exp_f32_e32 v224, v224
	v_exp_f32_e32 v225, v225
	v_exp_f32_e32 v226, v226
	v_exp_f32_e32 v227, v227
	v_exp_f32_e32 v228, v228
	v_exp_f32_e32 v229, v229
	v_exp_f32_e32 v230, v230
	v_exp_f32_e32 v231, v231
	v_exp_f32_e32 v232, v232
	v_exp_f32_e32 v233, v233
	v_exp_f32_e32 v234, v234
	v_exp_f32_e32 v235, v235
	s_cmp_lg_u32 s15, 32
	s_cbranch_scc1 .Ls2_nomask_1
	v_sub_u32_e32 v208, v147, v210
	v_cmp_le_i32_e32 vcc, 0, v208
	v_cmp_le_i32_e64 s[6:7], 1, v208
	s_nop 1
	v_cndmask_b32_e32 v220, 0, v220, vcc
	v_cndmask_b32_e64 v221, 0, v221, s[6:7]
	v_cmp_le_i32_e32 vcc, 2, v208
	v_cmp_le_i32_e64 s[6:7], 3, v208
	s_nop 1
	v_cndmask_b32_e32 v222, 0, v222, vcc
	v_cndmask_b32_e64 v223, 0, v223, s[6:7]
	v_cmp_le_i32_e32 vcc, 8, v208
	v_cmp_le_i32_e64 s[6:7], 9, v208
	s_nop 1
	v_cndmask_b32_e32 v224, 0, v224, vcc
	v_cndmask_b32_e64 v225, 0, v225, s[6:7]
	v_cmp_le_i32_e32 vcc, 10, v208
	v_cmp_le_i32_e64 s[6:7], 11, v208
	s_nop 1
	v_cndmask_b32_e32 v226, 0, v226, vcc
	v_cndmask_b32_e64 v227, 0, v227, s[6:7]
	v_cmp_le_i32_e32 vcc, 16, v208
	v_cmp_le_i32_e64 s[6:7], 17, v208
	s_nop 1
	v_cndmask_b32_e32 v228, 0, v228, vcc
	v_cndmask_b32_e64 v229, 0, v229, s[6:7]
	v_cmp_le_i32_e32 vcc, 18, v208
	v_cmp_le_i32_e64 s[6:7], 19, v208
	s_nop 1
	v_cndmask_b32_e32 v230, 0, v230, vcc
	v_cndmask_b32_e64 v231, 0, v231, s[6:7]
	v_cmp_le_i32_e32 vcc, 24, v208
	v_cmp_le_i32_e64 s[6:7], 25, v208
	s_nop 1
	v_cndmask_b32_e32 v232, 0, v232, vcc
	v_cndmask_b32_e64 v233, 0, v233, s[6:7]
	v_cmp_le_i32_e32 vcc, 26, v208
	v_cmp_le_i32_e64 s[6:7], 27, v208
	s_nop 1
	v_cndmask_b32_e32 v234, 0, v234, vcc
	v_cndmask_b32_e64 v235, 0, v235, s[6:7]
.Ls2_nomask_1:
	v_pk_mul_f32 v[20:21], v[20:21], v[220:221]
	v_pk_mul_f32 v[22:23], v[22:23], v[222:223]
	v_pk_mul_f32 v[24:25], v[24:25], v[224:225]
	v_pk_mul_f32 v[26:27], v[26:27], v[226:227]
	v_pk_mul_f32 v[28:29], v[28:29], v[228:229]
	v_pk_mul_f32 v[30:31], v[30:31], v[230:231]
	v_pk_mul_f32 v[32:33], v[32:33], v[232:233]
	v_pk_mul_f32 v[34:35], v[34:35], v[234:235]
	v_cvt_pk_bf16_f32 v244, v20, v21
	v_cvt_pk_bf16_f32 v245, v22, v23
	v_cvt_pk_bf16_f32 v246, v24, v25
	v_cvt_pk_bf16_f32 v247, v26, v27
	v_cvt_pk_bf16_f32 v248, v28, v29
	v_cvt_pk_bf16_f32 v249, v30, v31
	v_cvt_pk_bf16_f32 v250, v32, v33
	v_cvt_pk_bf16_f32 v251, v34, v35
	s_waitcnt lgkmcnt(0)
	s_nop 1
	v_mfma_f32_32x32x16_bf16 v[4:19], v[236:239], v[244:247], v[4:19]
	v_mfma_f32_32x32x16_bf16 v[4:19], v[240:243], v[248:251], v[4:19]
	s_add_i32 s15, s15, 32
	s_cmp_lg_u32 s15, 64
	s_cbranch_scc1 .LBB0_1038

.LBB0_1079:
	v_add_u32_e32 v208, 0x11000, v150
	v_add_u32_e32 v209, 0x23000, v2
	v_add_u32_e32 v210, s3, v160
	ds_read_b128 v[176:179], v208
	ds_read_b128 v[180:183], v208 offset:32
	ds_read_b128 v[184:187], v208 offset:64
	ds_read_b128 v[188:191], v208 offset:96
	ds_read_b128 v[192:195], v208 offset:128
	ds_read_b128 v[196:199], v208 offset:160
	ds_read_b128 v[200:203], v208 offset:192
	ds_read_b128 v[204:207], v208 offset:224
	ds_read_b128 v[220:223], v209
	ds_read_b128 v[224:227], v209 offset:32
	ds_read_b128 v[228:231], v209 offset:64
	ds_read_b128 v[232:235], v209 offset:96
	s_waitcnt lgkmcnt(11)
	v_mfma_f32_32x32x16_bf16 v[20:35], v[176:179], v[68:71], 0
	s_waitcnt lgkmcnt(10)
	v_mfma_f32_32x32x16_bf16 v[20:35], v[180:183], v[72:75], v[20:35]
	s_waitcnt lgkmcnt(9)
	v_mfma_f32_32x32x16_bf16 v[20:35], v[184:187], v[76:79], v[20:35]
	s_waitcnt lgkmcnt(8)
	v_mfma_f32_32x32x16_bf16 v[20:35], v[188:191], v[80:83], v[20:35]
	s_waitcnt lgkmcnt(7)
	v_mfma_f32_32x32x16_bf16 v[20:35], v[192:195], v[84:87], v[20:35]
	s_waitcnt lgkmcnt(6)
	v_mfma_f32_32x32x16_bf16 v[20:35], v[196:199], v[88:91], v[20:35]
	s_waitcnt lgkmcnt(5)
	v_mfma_f32_32x32x16_bf16 v[20:35], v[200:203], v[92:95], v[20:35]
	s_waitcnt lgkmcnt(4)
	v_mfma_f32_32x32x16_bf16 v[20:35], v[204:207], v[96:99], v[20:35]
	ds_read_b64_tr_b16 v[236:237], v151
	ds_read_b64_tr_b16 v[238:239], v151 offset:4352
	ds_read_b64_tr_b16 v[240:241], v151 offset:8704
	ds_read_b64_tr_b16 v[242:243], v151 offset:13056
	s_waitcnt lgkmcnt(4)
	v_pk_add_f32 v[220:221], v[154:155], v[220:221] op_sel:[1,0] op_sel_hi:[1,1] neg_lo:[0,1] neg_hi:[0,1]
	v_pk_add_f32 v[222:223], v[154:155], v[222:223] op_sel:[1,0] op_sel_hi:[1,1] neg_lo:[0,1] neg_hi:[0,1]
	v_pk_add_f32 v[224:225], v[154:155], v[224:225] op_sel:[1,0] op_sel_hi:[1,1] neg_lo:[0,1] neg_hi:[0,1]
	v_pk_add_f32 v[226:227], v[154:155], v[226:227] op_sel:[1,0] op_sel_hi:[1,1] neg_lo:[0,1] neg_hi:[0,1]
	v_pk_add_f32 v[228:229], v[154:155], v[228:229] op_sel:[1,0] op_sel_hi:[1,1] neg_lo:[0,1] neg_hi:[0,1]
	v_pk_add_f32 v[230:231], v[154:155], v[230:231] op_sel:[1,0] op_sel_hi:[1,1] neg_lo:[0,1] neg_hi:[0,1]
	v_pk_add_f32 v[232:233], v[154:155], v[232:233] op_sel:[1,0] op_sel_hi:[1,1] neg_lo:[0,1] neg_hi:[0,1]
	v_pk_add_f32 v[234:235], v[154:155], v[234:235] op_sel:[1,0] op_sel_hi:[1,1] neg_lo:[0,1] neg_hi:[0,1]
	v_exp_f32_e32 v220, v220
	v_exp_f32_e32 v221, v221
	v_exp_f32_e32 v222, v222
	v_exp_f32_e32 v223, v223
	v_exp_f32_e32 v224, v224
	v_exp_f32_e32 v225, v225
	v_exp_f32_e32 v226, v226
	v_exp_f32_e32 v227, v227
	v_exp_f32_e32 v228, v228
	v_exp_f32_e32 v229, v229
	v_exp_f32_e32 v230, v230
	v_exp_f32_e32 v231, v231
	v_exp_f32_e32 v232, v232
	v_exp_f32_e32 v233, v233
	v_exp_f32_e32 v234, v234
	v_exp_f32_e32 v235, v235
	s_cmp_lg_u32 s3, 64
	s_cbranch_scc1 .Ls2_nomask_2
	v_sub_u32_e32 v208, v156, v210
	v_cmp_le_i32_e32 vcc, 0, v208
	v_cmp_le_i32_e64 s[6:7], 1, v208
	s_nop 1
	v_cndmask_b32_e32 v220, 0, v220, vcc
	v_cndmask_b32_e64 v221, 0, v221, s[6:7]
	v_cmp_le_i32_e32 vcc, 2, v208
	v_cmp_le_i32_e64 s[6:7], 3, v208
	s_nop 1
	v_cndmask_b32_e32 v222, 0, v222, vcc
	v_cndmask_b32_e64 v223, 0, v223, s[6:7]
	v_cmp_le_i32_e32 vcc, 8, v208
	v_cmp_le_i32_e64 s[6:7], 9, v208
	s_nop 1
	v_cndmask_b32_e32 v224, 0, v224, vcc
	v_cndmask_b32_e64 v225, 0, v225, s[6:7]
	v_cmp_le_i32_e32 vcc, 10, v208
	v_cmp_le_i32_e64 s[6:7], 11, v208
	s_nop 1
	v_cndmask_b32_e32 v226, 0, v226, vcc
	v_cndmask_b32_e64 v227, 0, v227, s[6:7]
	v_cmp_le_i32_e32 vcc, 16, v208
	v_cmp_le_i32_e64 s[6:7], 17, v208
	s_nop 1
	v_cndmask_b32_e32 v228, 0, v228, vcc
	v_cndmask_b32_e64 v229, 0, v229, s[6:7]
	v_cmp_le_i32_e32 vcc, 18, v208
	v_cmp_le_i32_e64 s[6:7], 19, v208
	s_nop 1
	v_cndmask_b32_e32 v230, 0, v230, vcc
	v_cndmask_b32_e64 v231, 0, v231, s[6:7]
	v_cmp_le_i32_e32 vcc, 24, v208
	v_cmp_le_i32_e64 s[6:7], 25, v208
	s_nop 1
	v_cndmask_b32_e32 v232, 0, v232, vcc
	v_cndmask_b32_e64 v233, 0, v233, s[6:7]
	v_cmp_le_i32_e32 vcc, 26, v208
	v_cmp_le_i32_e64 s[6:7], 27, v208
	s_nop 1
	v_cndmask_b32_e32 v234, 0, v234, vcc
	v_cndmask_b32_e64 v235, 0, v235, s[6:7]
.Ls2_nomask_2:
	v_pk_mul_f32 v[20:21], v[20:21], v[220:221]
	v_pk_mul_f32 v[22:23], v[22:23], v[222:223]
	v_pk_mul_f32 v[24:25], v[24:25], v[224:225]
	v_pk_mul_f32 v[26:27], v[26:27], v[226:227]
	v_pk_mul_f32 v[28:29], v[28:29], v[228:229]
	v_pk_mul_f32 v[30:31], v[30:31], v[230:231]
	v_pk_mul_f32 v[32:33], v[32:33], v[232:233]
	v_pk_mul_f32 v[34:35], v[34:35], v[234:235]
	v_cvt_pk_bf16_f32 v244, v20, v21
	v_cvt_pk_bf16_f32 v245, v22, v23
	v_cvt_pk_bf16_f32 v246, v24, v25
	v_cvt_pk_bf16_f32 v247, v26, v27
	v_cvt_pk_bf16_f32 v248, v28, v29
	v_cvt_pk_bf16_f32 v249, v30, v31
	v_cvt_pk_bf16_f32 v250, v32, v33
	v_cvt_pk_bf16_f32 v251, v34, v35
	s_waitcnt lgkmcnt(0)
	s_nop 1
	v_mfma_f32_32x32x16_bf16 v[4:19], v[236:239], v[244:247], v[4:19]
	v_mfma_f32_32x32x16_bf16 v[4:19], v[240:243], v[248:251], v[4:19]
	s_add_i32 s3, s3, 32
	v_add_u32_e32 v151, 0x4400, v151
	v_add_u32_e32 v150, 0x2400, v150
	v_add_u32_e32 v2, 0x80, v2
	s_cmp_lg_u32 s3, 96
	s_cbranch_scc1 .LBB0_1079

.LBB0_1118:
	v_add_u32_e32 v208, 0x11000, v166
	v_add_u32_e32 v209, 0x23000, v167
	v_add_u32_e32 v210, s3, v160
	ds_read_b128 v[176:179], v208
	ds_read_b128 v[180:183], v208 offset:32
	ds_read_b128 v[184:187], v208 offset:64
	ds_read_b128 v[188:191], v208 offset:96
	ds_read_b128 v[192:195], v208 offset:128
	ds_read_b128 v[196:199], v208 offset:160
	ds_read_b128 v[200:203], v208 offset:192
	ds_read_b128 v[204:207], v208 offset:224
	ds_read_b128 v[220:223], v209
	ds_read_b128 v[224:227], v209 offset:32
	ds_read_b128 v[228:231], v209 offset:64
	ds_read_b128 v[232:235], v209 offset:96
	s_waitcnt lgkmcnt(11)
	v_mfma_f32_32x32x16_bf16 v[20:35], v[176:179], v[68:71], 0
	s_waitcnt lgkmcnt(10)
	v_mfma_f32_32x32x16_bf16 v[20:35], v[180:183], v[72:75], v[20:35]
	s_waitcnt lgkmcnt(9)
	v_mfma_f32_32x32x16_bf16 v[20:35], v[184:187], v[76:79], v[20:35]
	s_waitcnt lgkmcnt(8)
	v_mfma_f32_32x32x16_bf16 v[20:35], v[188:191], v[80:83], v[20:35]
	s_waitcnt lgkmcnt(7)
	v_mfma_f32_32x32x16_bf16 v[20:35], v[192:195], v[84:87], v[20:35]
	s_waitcnt lgkmcnt(6)
	v_mfma_f32_32x32x16_bf16 v[20:35], v[196:199], v[88:91], v[20:35]
	s_waitcnt lgkmcnt(5)
	v_mfma_f32_32x32x16_bf16 v[20:35], v[200:203], v[92:95], v[20:35]
	s_waitcnt lgkmcnt(4)
	v_mfma_f32_32x32x16_bf16 v[20:35], v[204:207], v[96:99], v[20:35]
	ds_read_b64_tr_b16 v[236:237], v165
	ds_read_b64_tr_b16 v[238:239], v165 offset:4352
	ds_read_b64_tr_b16 v[240:241], v165 offset:8704
	ds_read_b64_tr_b16 v[242:243], v165 offset:13056
	s_waitcnt lgkmcnt(4)
	v_pk_add_f32 v[220:221], v[2:3], v[220:221] op_sel_hi:[0,1] neg_lo:[0,1] neg_hi:[0,1]
	v_pk_add_f32 v[222:223], v[2:3], v[222:223] op_sel_hi:[0,1] neg_lo:[0,1] neg_hi:[0,1]
	v_pk_add_f32 v[224:225], v[2:3], v[224:225] op_sel_hi:[0,1] neg_lo:[0,1] neg_hi:[0,1]
	v_pk_add_f32 v[226:227], v[2:3], v[226:227] op_sel_hi:[0,1] neg_lo:[0,1] neg_hi:[0,1]
	v_pk_add_f32 v[228:229], v[2:3], v[228:229] op_sel_hi:[0,1] neg_lo:[0,1] neg_hi:[0,1]
	v_pk_add_f32 v[230:231], v[2:3], v[230:231] op_sel_hi:[0,1] neg_lo:[0,1] neg_hi:[0,1]
	v_pk_add_f32 v[232:233], v[2:3], v[232:233] op_sel_hi:[0,1] neg_lo:[0,1] neg_hi:[0,1]
	v_pk_add_f32 v[234:235], v[2:3], v[234:235] op_sel_hi:[0,1] neg_lo:[0,1] neg_hi:[0,1]
	v_exp_f32_e32 v220, v220
	v_exp_f32_e32 v221, v221
	v_exp_f32_e32 v222, v222
	v_exp_f32_e32 v223, v223
	v_exp_f32_e32 v224, v224
	v_exp_f32_e32 v225, v225
	v_exp_f32_e32 v226, v226
	v_exp_f32_e32 v227, v227
	v_exp_f32_e32 v228, v228
	v_exp_f32_e32 v229, v229
	v_exp_f32_e32 v230, v230
	v_exp_f32_e32 v231, v231
	v_exp_f32_e32 v232, v232
	v_exp_f32_e32 v233, v233
	v_exp_f32_e32 v234, v234
	v_exp_f32_e32 v235, v235
	s_cmp_lg_u32 s3, 96
	s_cbranch_scc1 .Ls2_nomask_3
	v_sub_u32_e32 v208, v36, v210
	v_cmp_le_i32_e32 vcc, 0, v208
	v_cmp_le_i32_e64 s[6:7], 1, v208
	s_nop 1
	v_cndmask_b32_e32 v220, 0, v220, vcc
	v_cndmask_b32_e64 v221, 0, v221, s[6:7]
	v_cmp_le_i32_e32 vcc, 2, v208
	v_cmp_le_i32_e64 s[6:7], 3, v208
	s_nop 1
	v_cndmask_b32_e32 v222, 0, v222, vcc
	v_cndmask_b32_e64 v223, 0, v223, s[6:7]
	v_cmp_le_i32_e32 vcc, 8, v208
	v_cmp_le_i32_e64 s[6:7], 9, v208
	s_nop 1
	v_cndmask_b32_e32 v224, 0, v224, vcc
	v_cndmask_b32_e64 v225, 0, v225, s[6:7]
	v_cmp_le_i32_e32 vcc, 10, v208
	v_cmp_le_i32_e64 s[6:7], 11, v208
	s_nop 1
	v_cndmask_b32_e32 v226, 0, v226, vcc
	v_cndmask_b32_e64 v227, 0, v227, s[6:7]
	v_cmp_le_i32_e32 vcc, 16, v208
	v_cmp_le_i32_e64 s[6:7], 17, v208
	s_nop 1
	v_cndmask_b32_e32 v228, 0, v228, vcc
	v_cndmask_b32_e64 v229, 0, v229, s[6:7]
	v_cmp_le_i32_e32 vcc, 18, v208
	v_cmp_le_i32_e64 s[6:7], 19, v208
	s_nop 1
	v_cndmask_b32_e32 v230, 0, v230, vcc
	v_cndmask_b32_e64 v231, 0, v231, s[6:7]
	v_cmp_le_i32_e32 vcc, 24, v208
	v_cmp_le_i32_e64 s[6:7], 25, v208
	s_nop 1
	v_cndmask_b32_e32 v232, 0, v232, vcc
	v_cndmask_b32_e64 v233, 0, v233, s[6:7]
	v_cmp_le_i32_e32 vcc, 26, v208
	v_cmp_le_i32_e64 s[6:7], 27, v208
	s_nop 1
	v_cndmask_b32_e32 v234, 0, v234, vcc
	v_cndmask_b32_e64 v235, 0, v235, s[6:7]
.Ls2_nomask_3:
	v_pk_mul_f32 v[20:21], v[20:21], v[220:221]
	v_pk_mul_f32 v[22:23], v[22:23], v[222:223]
	v_pk_mul_f32 v[24:25], v[24:25], v[224:225]
	v_pk_mul_f32 v[26:27], v[26:27], v[226:227]
	v_pk_mul_f32 v[28:29], v[28:29], v[228:229]
	v_pk_mul_f32 v[30:31], v[30:31], v[230:231]
	v_pk_mul_f32 v[32:33], v[32:33], v[232:233]
	v_pk_mul_f32 v[34:35], v[34:35], v[234:235]
	v_cvt_pk_bf16_f32 v244, v20, v21
	v_cvt_pk_bf16_f32 v245, v22, v23
	v_cvt_pk_bf16_f32 v246, v24, v25
	v_cvt_pk_bf16_f32 v247, v26, v27
	v_cvt_pk_bf16_f32 v248, v28, v29
	v_cvt_pk_bf16_f32 v249, v30, v31
	v_cvt_pk_bf16_f32 v250, v32, v33
	v_cvt_pk_bf16_f32 v251, v34, v35
	s_waitcnt lgkmcnt(0)
	s_nop 1
	v_mfma_f32_32x32x16_bf16 v[4:19], v[236:239], v[244:247], v[4:19]
	v_mfma_f32_32x32x16_bf16 v[4:19], v[240:243], v[248:251], v[4:19]
	s_add_i32 s3, s3, 32
	v_add_u32_e32 v165, 0x4400, v165
	v_add_u32_e32 v166, 0x2400, v166
	v_add_u32_e32 v167, 0x80, v167
	s_cmp_lg_u32 s3, 128
	s_cbranch_scc1 .LBB0_1118
